# SwiGLU GEMM: unit after an epilogue enters through a peeled pair of super-phases whose counted waits leave the 8 epilogue stores in flight
# speedup vs baseline: 1.0136x; 1.0021x over previous
; #define GETLANE() int lane; asm volatile("v_mbcnt_lo_u32_b32 %0, -1, 0\n\tv_mbcnt_hi_u32_b32 %0, -1, %0" : "=v"(lane)); const int tid = wave * 64 + lane
;     __device__ __forceinline__ bool next(int i, pg8::Unit& u) const {
;         const int L = i * G + c;
;         if (L < n_lat) {
;             const int wgid = (L & 7) * (n_lat >> 3) + (L >> 3), nig = 8 * nN, w = wgid % nig;
;             u.pm = (((wgid / nig) ^ (ksplit >> 8)) * 8 + (w & 7)) | (ntfull << 16); u.pn = w >> 3; return true; }
;         const int q = L - n_lat; if (q >= n_ctx) return false;
;         const int ksp = ksplit & 0xff, ks = q % ksp, rest = q / ksp; u.pn = (rest % nN) | (ks << 16) | (ksp > 1 ? (1 << 30) : 0); u.pm = (128 + rest / nN) | ((ntfull / ksp) << 16); return true;
; __global__ void __launch_bounds__(NTHR) fwd_megakernel(Args a_unused) {
;     ...
;             else if (j == 1 || j == 11) {
;                 GETLANE(); (void)lane;
;                 pg8::Gemm g{XN, (const bf16_t*)(wb + (j == 1 ? W_FFN1_IN : W_FFN2_IN)), MTOT, 2 * DFF, D}; CtxOrder S; S.init(2 * DFF, D, G, bid, nctx, 1);
;                 EpiSwiGLU E{(bf16_t*)(ws + OFF_HFF)}; pg8::gemm_phase<EpiSwiGLU, CtxOrder, true, true>(lds, g, S, E, tid); }
.LBB0_83:
	s_mov_b32 s93, 0
	v_readlane_b32 s0, v254, 48
	v_mbcnt_lo_u32_b32 v10, -1, 0
	v_mbcnt_hi_u32_b32 v10, -1, v10
	s_mul_i32 s46, s46, 22
	s_cmpk_gt_i32 s89, 0xaff
	v_lshl_add_u32 v1, s0, 6, v10
	s_nop 0
	v_readfirstlane_b32 s14, v1
	s_cbranch_scc0 .LBB0_88
	s_add_i32 s0, s89, 0xfffff500
	s_mov_b64 s[2:3], 0
	s_cmp_lt_u32 s0, s46
	s_mov_b64 s[0:1], 0
	s_cbranch_scc0 .LBB0_86
	s_bfe_u32 s0, s89, 0x70001
	s_mulk_i32 s0, 0xbb
	s_bfe_u32 s0, s0, 0x5000b
	s_mul_i32 s1, s0, 22
	s_sub_i32 s1, s89, s1
	s_and_b32 s57, s1, 0xff
	s_or_b32 s58, s0, 0x100080
	s_mov_b64 s[0:1], -1
	s_and_b64 vcc, exec, s[2:3]
	s_cbranch_vccz .LBB0_89
	s_branch .LBB0_87

; #define PG8_STAGE(bufoff, gbase, voff) do { _Pragma("unroll") for (int _i = 0; _i < 2; ++_i) \
;         __builtin_amdgcn_global_load_lds((const unsigned*)((const char*)(gbase) + (voff)[_i]), (PG8_LAS unsigned*)(lds + (bufoff) + ldsw + _i * 8192), 16, 0, 0); } while (0)
; #define PG8_LDA(dst, b, h) do { _Pragma("unroll") for (int m = 0; m < 4; ++m) _Pragma("unroll") for (int k = 0; k < 2; ++k) dst[m][k] = *(const PG8_LAS bf16x8*)(lds + PG8_SA(b, h) + aoff + m * 2048 + k * 1024); } while (0)
; #define PG8_LDB(dst, b, h) do { _Pragma("unroll") for (int n = 0; n < 2; ++n) _Pragma("unroll") for (int k = 0; k < 2; ++k) dst[n][k] = *(const PG8_LAS bf16x8*)(lds + PG8_SB(b, h) + boff + n * 2048 + k * 1024); } while (0)
; #define PG8_WAIT_V(n) asm volatile("s_waitcnt vmcnt(" #n ")" ::: "memory")
; #define PG8_WAIT_L(n) asm volatile("s_waitcnt lgkmcnt(" #n ")" ::: "memory")
; #define PG8_BAR __builtin_amdgcn_s_barrier()
; #define PG8_SCHED __builtin_amdgcn_sched_barrier(0)
; template <class Epi, class Sched, bool ALIGN_EPI = false, bool SP2 = false>
; __device__ __forceinline__ void gemm_phase(PG8_LAS unsigned char* lds, const Gemm g, const Sched& S, const Epi& E, const int tid_in) {
;     ...
;             PG8_LDB(B0, 0, 0); PG8_LDB(B1, 0, 1); PG8_SCHED; PG8_LDA(At, 0, 0); PG8_STAGE(PG8_SA(1, 1), a1 + hstep, voffA);
;             PG8_WAIT_V(8); PG8_WAIT_L(0); PG8_BAR; PG8_MMA(0, 0, At, B0); PG8_MMA(0, 1, At, B1); PG8_BAR; PG8_SCHED;
;     ...
; #pragma unroll
;         for (int a = 0; a < 2; ++a)
; #pragma unroll
;             for (int b = 0; b < 2; ++b)
; #pragma unroll
;                 for (int m = 0; m < 4; ++m)
; #pragma unroll
;                     for (int n = 0; n < 2; ++n) acc[a][b][m][n] = (f32x4){0.f, 0.f, 0.f, 0.f};
;         cur = nxt; cA = nA; cB = nB; ++ui;
.LBB0_103:
	s_add_i32 s59, s16, -2
	s_add_u32 s28, s28, 0x40080
	s_addc_u32 s29, s29, 0
	s_add_u32 s60, s34, 0x100
	v_mov_b32_e32 v2, 0
	s_addc_u32 s61, s35, 0
	s_mov_b32 s34, 0
	v_mov_b32_e32 v3, v2
	v_mov_b32_e32 v4, v2
	v_mov_b32_e32 v5, v2
	v_mov_b32_e32 v10, v2
	v_mov_b32_e32 v11, v2
	v_mov_b32_e32 v12, v2
	v_mov_b32_e32 v13, v2
	v_mov_b32_e32 v18, v2
	v_mov_b32_e32 v19, v2
	v_mov_b32_e32 v20, v2
	v_mov_b32_e32 v21, v2
	v_mov_b32_e32 v26, v2
	v_mov_b32_e32 v27, v2
	v_mov_b32_e32 v28, v2
	v_mov_b32_e32 v29, v2
	v_mov_b32_e32 v34, v2
	v_mov_b32_e32 v35, v2
	v_mov_b32_e32 v36, v2
	v_mov_b32_e32 v37, v2
	v_mov_b32_e32 v42, v2
	v_mov_b32_e32 v43, v2
	v_mov_b32_e32 v44, v2
	v_mov_b32_e32 v45, v2
	v_mov_b32_e32 v50, v2
	v_mov_b32_e32 v51, v2
	v_mov_b32_e32 v52, v2
	v_mov_b32_e32 v53, v2
	v_mov_b32_e32 v58, v2
	v_mov_b32_e32 v59, v2
	v_mov_b32_e32 v60, v2
	v_mov_b32_e32 v61, v2
	v_mov_b32_e32 v6, v2
	v_mov_b32_e32 v7, v2
	v_mov_b32_e32 v8, v2
	v_mov_b32_e32 v9, v2
	v_mov_b32_e32 v14, v2
	v_mov_b32_e32 v15, v2
	v_mov_b32_e32 v16, v2
	v_mov_b32_e32 v17, v2
	v_mov_b32_e32 v22, v2
	v_mov_b32_e32 v23, v2
	v_mov_b32_e32 v24, v2
	v_mov_b32_e32 v25, v2
	v_mov_b32_e32 v30, v2
	v_mov_b32_e32 v31, v2
	v_mov_b32_e32 v32, v2
	v_mov_b32_e32 v33, v2
	v_mov_b32_e32 v38, v2
	v_mov_b32_e32 v39, v2
	v_mov_b32_e32 v40, v2
	v_mov_b32_e32 v41, v2
	v_mov_b32_e32 v46, v2
	v_mov_b32_e32 v47, v2
	v_mov_b32_e32 v48, v2
	v_mov_b32_e32 v49, v2
	v_mov_b32_e32 v54, v2
	v_mov_b32_e32 v55, v2
	v_mov_b32_e32 v56, v2
	v_mov_b32_e32 v57, v2
	v_mov_b32_e32 v62, v2
	v_mov_b32_e32 v63, v2
	v_mov_b32_e32 v64, v2
	v_mov_b32_e32 v65, v2
	v_mov_b32_e32 v66, v2
	v_mov_b32_e32 v67, v2
	v_mov_b32_e32 v68, v2
	v_mov_b32_e32 v69, v2
	v_mov_b32_e32 v74, v2
	v_mov_b32_e32 v75, v2
	v_mov_b32_e32 v76, v2
	v_mov_b32_e32 v77, v2
	v_mov_b32_e32 v82, v2
	v_mov_b32_e32 v83, v2
	v_mov_b32_e32 v84, v2
	v_mov_b32_e32 v85, v2
	v_mov_b32_e32 v90, v2
	v_mov_b32_e32 v91, v2
	v_mov_b32_e32 v92, v2
	v_mov_b32_e32 v93, v2
	v_mov_b32_e32 v98, v2
	v_mov_b32_e32 v99, v2
	v_mov_b32_e32 v100, v2
	v_mov_b32_e32 v101, v2
	v_mov_b32_e32 v106, v2
	v_mov_b32_e32 v107, v2
	v_mov_b32_e32 v108, v2
	v_mov_b32_e32 v109, v2
	v_mov_b32_e32 v114, v2
	v_mov_b32_e32 v115, v2
	v_mov_b32_e32 v116, v2
	v_mov_b32_e32 v117, v2
	v_mov_b32_e32 v122, v2
	v_mov_b32_e32 v123, v2
	v_mov_b32_e32 v124, v2
	v_mov_b32_e32 v125, v2
	v_mov_b32_e32 v70, v2
	v_mov_b32_e32 v71, v2
	v_mov_b32_e32 v72, v2
	v_mov_b32_e32 v73, v2
	v_mov_b32_e32 v78, v2
	v_mov_b32_e32 v79, v2
	v_mov_b32_e32 v80, v2
	v_mov_b32_e32 v81, v2
	v_mov_b32_e32 v86, v2
	v_mov_b32_e32 v87, v2
	v_mov_b32_e32 v88, v2
	v_mov_b32_e32 v89, v2
	v_mov_b32_e32 v94, v2
	v_mov_b32_e32 v95, v2
	v_mov_b32_e32 v96, v2
	v_mov_b32_e32 v97, v2
	v_mov_b32_e32 v102, v2
	v_mov_b32_e32 v103, v2
	v_mov_b32_e32 v104, v2
	v_mov_b32_e32 v105, v2
	v_mov_b32_e32 v110, v2
	v_mov_b32_e32 v111, v2
	v_mov_b32_e32 v112, v2
	v_mov_b32_e32 v113, v2
	v_mov_b32_e32 v118, v2
	v_mov_b32_e32 v119, v2
	v_mov_b32_e32 v120, v2
	v_mov_b32_e32 v121, v2
	v_mov_b32_e32 v126, v2
	v_mov_b32_e32 v127, v2
	v_mov_b32_e32 v128, v2
	v_mov_b32_e32 v129, v2
	s_cmp_eq_u32 s93, 1
	s_cbranch_scc0 .LBB0_104
	s_add_i32 s62, s34, 2
	s_add_u32 s35, s28, 0xfffc0080
	s_addc_u32 s40, s29, -1
	s_add_i32 s63, 0, 0x10000
	s_cmp_eq_u32 s59, s34
	s_cselect_b32 s41, s21, s40
	s_cselect_b32 s40, s20, s35
	v_add_u32_e32 v145, s63, v143
	s_cselect_b32 s35, s27, s61
	s_cselect_b32 s34, s26, s60
	s_add_i32 s66, 0, 0x14000
	ds_read_b128 v[146:149], v145
	ds_read_b128 v[150:153], v145 offset:1024
	ds_read_b128 v[154:157], v145 offset:2048
	ds_read_b128 v[158:161], v145 offset:3072
	v_add_u32_e32 v145, s66, v143
	ds_read_b128 v[162:165], v145
	ds_read_b128 v[166:169], v145 offset:1024
	ds_read_b128 v[170:173], v145 offset:2048
	ds_read_b128 v[174:177], v145 offset:3072
	v_lshl_add_u64 v[218:219], s[28:29], 0, v[138:139]
	s_add_i32 m0, s45, 0xc000
	ds_read_b128 v[178:181], v144
	ds_read_b128 v[182:185], v144 offset:1024
	ds_read_b128 v[186:189], v144 offset:2048
	ds_read_b128 v[192:195], v144 offset:3072
	ds_read_b128 v[196:199], v144 offset:4096
	ds_read_b128 v[200:203], v144 offset:5120
	ds_read_b128 v[230:233], v144 offset:6144
	ds_read_b128 v[234:237], v144 offset:7168
	global_load_lds_dwordx4 v[218:219], off
	v_lshl_add_u64 v[218:219], s[28:29], 0, v[140:141]
	s_add_i32 m0, s45, 0xe000
	s_nop 0
	global_load_lds_dwordx4 v[218:219], off
	s_waitcnt vmcnt(16)
	s_waitcnt lgkmcnt(0)
	s_barrier
	s_setprio 1
	s_waitcnt lgkmcnt(0)
	v_mfma_f32_16x16x32_f16 v[126:129], v[146:149], v[178:181], v[126:129]
	v_mfma_f32_16x16x32_f16 v[118:121], v[154:157], v[178:181], v[118:121]
	v_mfma_f32_16x16x32_f16 v[110:113], v[146:149], v[186:189], v[110:113]
	v_mfma_f32_16x16x32_f16 v[102:105], v[154:157], v[186:189], v[102:105]
	v_mfma_f32_16x16x32_f16 v[94:97], v[146:149], v[196:199], v[94:97]
	v_mfma_f32_16x16x32_f16 v[86:89], v[154:157], v[196:199], v[86:89]
	v_mfma_f32_16x16x32_f16 v[78:81], v[146:149], v[230:233], v[78:81]
	v_mfma_f32_16x16x32_f16 v[70:73], v[154:157], v[230:233], v[70:73]
	v_mfma_f32_16x16x32_f16 v[126:129], v[150:153], v[182:185], v[126:129]
	v_mfma_f32_16x16x32_f16 v[118:121], v[158:161], v[182:185], v[118:121]
	v_mfma_f32_16x16x32_f16 v[110:113], v[150:153], v[192:195], v[110:113]
	v_mfma_f32_16x16x32_f16 v[102:105], v[158:161], v[192:195], v[102:105]
	v_mfma_f32_16x16x32_f16 v[94:97], v[150:153], v[200:203], v[94:97]
	v_mfma_f32_16x16x32_f16 v[86:89], v[158:161], v[200:203], v[86:89]
	v_mfma_f32_16x16x32_f16 v[78:81], v[150:153], v[234:237], v[78:81]
	v_mfma_f32_16x16x32_f16 v[70:73], v[158:161], v[234:237], v[70:73]
	s_setprio 0
	s_setprio 1
	v_mfma_f32_16x16x32_f16 v[122:125], v[162:165], v[178:181], v[122:125]
	v_mfma_f32_16x16x32_f16 v[114:117], v[170:173], v[178:181], v[114:117]
	v_mfma_f32_16x16x32_f16 v[106:109], v[162:165], v[186:189], v[106:109]
	v_mfma_f32_16x16x32_f16 v[98:101], v[170:173], v[186:189], v[98:101]
	v_mfma_f32_16x16x32_f16 v[90:93], v[162:165], v[196:199], v[90:93]
	v_mfma_f32_16x16x32_f16 v[82:85], v[170:173], v[196:199], v[82:85]
	v_mfma_f32_16x16x32_f16 v[74:77], v[162:165], v[230:233], v[74:77]
	v_mfma_f32_16x16x32_f16 v[66:69], v[170:173], v[230:233], v[66:69]
	v_mfma_f32_16x16x32_f16 v[122:125], v[166:169], v[182:185], v[122:125]
	v_mfma_f32_16x16x32_f16 v[114:117], v[174:177], v[182:185], v[114:117]
	v_mfma_f32_16x16x32_f16 v[106:109], v[166:169], v[192:195], v[106:109]
	v_mfma_f32_16x16x32_f16 v[98:101], v[174:177], v[192:195], v[98:101]
	v_mfma_f32_16x16x32_f16 v[90:93], v[166:169], v[200:203], v[90:93]
	v_mfma_f32_16x16x32_f16 v[82:85], v[174:177], v[200:203], v[82:85]
	v_mfma_f32_16x16x32_f16 v[74:77], v[166:169], v[234:237], v[74:77]
	v_mfma_f32_16x16x32_f16 v[66:69], v[174:177], v[234:237], v[66:69]
	s_setprio 0
	s_barrier
; #define PG8_STAGE(bufoff, gbase, voff) do { _Pragma("unroll") for (int _i = 0; _i < 2; ++_i) \
;         __builtin_amdgcn_global_load_lds((const unsigned*)((const char*)(gbase) + (voff)[_i]), (PG8_LAS unsigned*)(lds + (bufoff) + ldsw + _i * 8192), 16, 0, 0); } while (0)
; #define PG8_LDA(dst, b, h) do { _Pragma("unroll") for (int m = 0; m < 4; ++m) _Pragma("unroll") for (int k = 0; k < 2; ++k) dst[m][k] = *(const PG8_LAS bf16x8*)(lds + PG8_SA(b, h) + aoff + m * 2048 + k * 1024); } while (0)
; #define PG8_LDB(dst, b, h) do { _Pragma("unroll") for (int n = 0; n < 2; ++n) _Pragma("unroll") for (int k = 0; k < 2; ++k) dst[n][k] = *(const PG8_LAS bf16x8*)(lds + PG8_SB(b, h) + boff + n * 2048 + k * 1024); } while (0)
; #define PG8_WAIT_V(n) asm volatile("s_waitcnt vmcnt(" #n ")" ::: "memory")
; #define PG8_WAIT_L(n) asm volatile("s_waitcnt lgkmcnt(" #n ")" ::: "memory")
; #define PG8_BAR __builtin_amdgcn_s_barrier()
; #define PG8_SCHED __builtin_amdgcn_sched_barrier(0)
; template <class Epi, class Sched, bool ALIGN_EPI = false, bool SP2 = false>
; __device__ __forceinline__ void gemm_phase(PG8_LAS unsigned char* lds, const Gemm g, const Sched& S, const Epi& E, const int tid_in) {
;     ...
;             PG8_LDB(B0, 0, 0); PG8_LDB(B1, 0, 1); PG8_SCHED; PG8_LDA(At, 0, 0); PG8_STAGE(PG8_SA(1, 1), a1 + hstep, voffA);
;             PG8_WAIT_V(8); PG8_WAIT_L(0); PG8_BAR; PG8_MMA(0, 0, At, B0); PG8_MMA(0, 1, At, B1); PG8_BAR; PG8_SCHED;
;             PG8_LDA(At, 0, 1); PG8_STAGE(PG8_SB(0, 0), b2, voffB); PG8_STAGE(PG8_SB(0, 1), b2 + hstep, voffB); PG8_STAGE(PG8_SA(0, 0), a2, voffA);
;             PG8_WAIT_V(8); PG8_WAIT_L(0); PG8_BAR; PG8_MMA(1, 0, At, B0); PG8_MMA(1, 1, At, B1); PG8_BAR; PG8_SCHED;
	s_add_i32 s63, s63, s44
	v_lshl_add_u64 v[218:219], s[34:35], 0, v[132:133]
	s_mov_b32 m0, s63
	ds_read_b128 v[178:181], v144 offset:16384
	ds_read_b128 v[182:185], v144 offset:17408
	ds_read_b128 v[186:189], v144 offset:18432
	ds_read_b128 v[192:195], v144 offset:19456
	ds_read_b128 v[196:199], v144 offset:20480
	ds_read_b128 v[200:203], v144 offset:21504
	ds_read_b128 v[230:233], v144 offset:22528
	ds_read_b128 v[234:237], v144 offset:23552
	global_load_lds_dwordx4 v[218:219], off
	s_add_i32 m0, s63, 0x2000
	s_add_u32 s64, s34, 0x40000
	v_lshl_add_u64 v[220:221], s[34:35], 0, v[136:137]
	s_addc_u32 s65, s35, 0
	s_add_i32 s63, s66, s44
	global_load_lds_dwordx4 v[220:221], off
	v_lshl_add_u64 v[222:223], s[64:65], 0, v[132:133]
	s_mov_b32 m0, s63
	v_lshl_add_u64 v[224:225], s[40:41], 0, v[134:135]
	global_load_lds_dwordx4 v[222:223], off
	v_lshl_add_u64 v[222:223], s[64:65], 0, v[136:137]
	s_add_i32 m0, s63, 0x2000
	s_nop 0
	global_load_lds_dwordx4 v[222:223], off
	v_lshl_add_u64 v[222:223], s[40:41], 0, v[130:131]
	s_mov_b32 m0, s45
	s_nop 0
	global_load_lds_dwordx4 v[222:223], off
	s_mov_b32 m0, s47
	s_nop 0
	global_load_lds_dwordx4 v[224:225], off
	s_waitcnt vmcnt(16)
	s_waitcnt lgkmcnt(0)
	s_barrier
	s_setprio 1
	s_waitcnt lgkmcnt(0)
	v_mfma_f32_16x16x32_f16 v[62:65], v[146:149], v[178:181], v[62:65]
	v_mfma_f32_16x16x32_f16 v[54:57], v[154:157], v[178:181], v[54:57]
	v_mfma_f32_16x16x32_f16 v[46:49], v[146:149], v[186:189], v[46:49]
	v_mfma_f32_16x16x32_f16 v[38:41], v[154:157], v[186:189], v[38:41]
	v_mfma_f32_16x16x32_f16 v[30:33], v[146:149], v[196:199], v[30:33]
	v_mfma_f32_16x16x32_f16 v[22:25], v[154:157], v[196:199], v[22:25]
	v_mfma_f32_16x16x32_f16 v[14:17], v[146:149], v[230:233], v[14:17]
	v_mfma_f32_16x16x32_f16 v[6:9], v[154:157], v[230:233], v[6:9]
	v_mfma_f32_16x16x32_f16 v[62:65], v[150:153], v[182:185], v[62:65]
	v_mfma_f32_16x16x32_f16 v[54:57], v[158:161], v[182:185], v[54:57]
	v_mfma_f32_16x16x32_f16 v[46:49], v[150:153], v[192:195], v[46:49]
	v_mfma_f32_16x16x32_f16 v[38:41], v[158:161], v[192:195], v[38:41]
	v_mfma_f32_16x16x32_f16 v[30:33], v[150:153], v[200:203], v[30:33]
	v_mfma_f32_16x16x32_f16 v[22:25], v[158:161], v[200:203], v[22:25]
	v_mfma_f32_16x16x32_f16 v[14:17], v[150:153], v[234:237], v[14:17]
	v_mfma_f32_16x16x32_f16 v[6:9], v[158:161], v[234:237], v[6:9]
	s_setprio 0
	s_setprio 1
	v_mfma_f32_16x16x32_f16 v[58:61], v[162:165], v[178:181], v[58:61]
	v_mfma_f32_16x16x32_f16 v[50:53], v[170:173], v[178:181], v[50:53]
	v_mfma_f32_16x16x32_f16 v[42:45], v[162:165], v[186:189], v[42:45]
	v_mfma_f32_16x16x32_f16 v[34:37], v[170:173], v[186:189], v[34:37]
	v_mfma_f32_16x16x32_f16 v[26:29], v[162:165], v[196:199], v[26:29]
	v_mfma_f32_16x16x32_f16 v[18:21], v[170:173], v[196:199], v[18:21]
	v_mfma_f32_16x16x32_f16 v[10:13], v[162:165], v[230:233], v[10:13]
	v_mfma_f32_16x16x32_f16 v[2:5], v[170:173], v[230:233], v[2:5]
	v_mfma_f32_16x16x32_f16 v[58:61], v[166:169], v[182:185], v[58:61]
	v_mfma_f32_16x16x32_f16 v[50:53], v[174:177], v[182:185], v[50:53]
	v_mfma_f32_16x16x32_f16 v[42:45], v[166:169], v[192:195], v[42:45]
	v_mfma_f32_16x16x32_f16 v[34:37], v[174:177], v[192:195], v[34:37]
	v_mfma_f32_16x16x32_f16 v[26:29], v[166:169], v[200:203], v[26:29]
	v_mfma_f32_16x16x32_f16 v[18:21], v[174:177], v[200:203], v[18:21]
	v_mfma_f32_16x16x32_f16 v[10:13], v[166:169], v[234:237], v[10:13]
	v_mfma_f32_16x16x32_f16 v[2:5], v[174:177], v[234:237], v[2:5]
	s_setprio 0
	s_barrier
	s_branch .Lmid_104
.LBB0_104:
	s_add_i32 s62, s34, 2
	s_add_u32 s35, s28, 0xfffc0080
	s_addc_u32 s40, s29, -1
	s_add_i32 s63, 0, 0x10000
	s_cmp_eq_u32 s59, s34
	s_cselect_b32 s41, s21, s40
	s_cselect_b32 s40, s20, s35
	v_add_u32_e32 v145, s63, v143
	s_cselect_b32 s35, s27, s61
	s_cselect_b32 s34, s26, s60
	s_add_i32 s66, 0, 0x14000
	ds_read_b128 v[146:149], v145
	ds_read_b128 v[150:153], v145 offset:1024
	ds_read_b128 v[154:157], v145 offset:2048
	ds_read_b128 v[158:161], v145 offset:3072
	v_add_u32_e32 v145, s66, v143
	ds_read_b128 v[162:165], v145
	ds_read_b128 v[166:169], v145 offset:1024
	ds_read_b128 v[170:173], v145 offset:2048
	ds_read_b128 v[174:177], v145 offset:3072
	v_lshl_add_u64 v[218:219], s[28:29], 0, v[138:139]
	s_add_i32 m0, s45, 0xc000
	ds_read_b128 v[178:181], v144
	ds_read_b128 v[182:185], v144 offset:1024
	ds_read_b128 v[186:189], v144 offset:2048
	ds_read_b128 v[192:195], v144 offset:3072
	ds_read_b128 v[196:199], v144 offset:4096
	ds_read_b128 v[200:203], v144 offset:5120
	ds_read_b128 v[230:233], v144 offset:6144
	ds_read_b128 v[234:237], v144 offset:7168
	global_load_lds_dwordx4 v[218:219], off
	v_lshl_add_u64 v[218:219], s[28:29], 0, v[140:141]
	s_add_i32 m0, s45, 0xe000
	s_nop 0
	global_load_lds_dwordx4 v[218:219], off
	s_waitcnt vmcnt(8)
	s_waitcnt lgkmcnt(0)
	s_barrier
; #define PG8_STAGE(bufoff, gbase, voff) do { _Pragma("unroll") for (int _i = 0; _i < 2; ++_i) \
;         __builtin_amdgcn_global_load_lds((const unsigned*)((const char*)(gbase) + (voff)[_i]), (PG8_LAS unsigned*)(lds + (bufoff) + ldsw + _i * 8192), 16, 0, 0); } while (0)
; #define PG8_LDA(dst, b, h) do { _Pragma("unroll") for (int m = 0; m < 4; ++m) _Pragma("unroll") for (int k = 0; k < 2; ++k) dst[m][k] = *(const PG8_LAS bf16x8*)(lds + PG8_SA(b, h) + aoff + m * 2048 + k * 1024); } while (0)
; #define PG8_LDB(dst, b, h) do { _Pragma("unroll") for (int n = 0; n < 2; ++n) _Pragma("unroll") for (int k = 0; k < 2; ++k) dst[n][k] = *(const PG8_LAS bf16x8*)(lds + PG8_SB(b, h) + boff + n * 2048 + k * 1024); } while (0)
; #define PG8_WAIT_V(n) asm volatile("s_waitcnt vmcnt(" #n ")" ::: "memory")
; #define PG8_WAIT_L(n) asm volatile("s_waitcnt lgkmcnt(" #n ")" ::: "memory")
; #define PG8_BAR __builtin_amdgcn_s_barrier()
; #define PG8_SCHED __builtin_amdgcn_sched_barrier(0)
; template <class Epi, class Sched, bool ALIGN_EPI = false, bool SP2 = false>
; __device__ __forceinline__ void gemm_phase(PG8_LAS unsigned char* lds, const Gemm g, const Sched& S, const Epi& E, const int tid_in) {
;     ...
;             PG8_LDB(B0, 0, 0); PG8_LDB(B1, 0, 1); PG8_SCHED; PG8_LDA(At, 0, 0); PG8_STAGE(PG8_SA(1, 1), a1 + hstep, voffA);
;             PG8_WAIT_V(8); PG8_WAIT_L(0); PG8_BAR; PG8_MMA(0, 0, At, B0); PG8_MMA(0, 1, At, B1); PG8_BAR; PG8_SCHED;
;             PG8_LDA(At, 0, 1); PG8_STAGE(PG8_SB(0, 0), b2, voffB); PG8_STAGE(PG8_SB(0, 1), b2 + hstep, voffB); PG8_STAGE(PG8_SA(0, 0), a2, voffA);
;             PG8_WAIT_V(8); PG8_WAIT_L(0); PG8_BAR; PG8_MMA(1, 0, At, B0); PG8_MMA(1, 1, At, B1); PG8_BAR; PG8_SCHED;
	s_setprio 1
	s_waitcnt lgkmcnt(0)
	v_mfma_f32_16x16x32_f16 v[126:129], v[146:149], v[178:181], v[126:129]
	v_mfma_f32_16x16x32_f16 v[118:121], v[154:157], v[178:181], v[118:121]
	v_mfma_f32_16x16x32_f16 v[110:113], v[146:149], v[186:189], v[110:113]
	v_mfma_f32_16x16x32_f16 v[102:105], v[154:157], v[186:189], v[102:105]
	v_mfma_f32_16x16x32_f16 v[94:97], v[146:149], v[196:199], v[94:97]
	v_mfma_f32_16x16x32_f16 v[86:89], v[154:157], v[196:199], v[86:89]
	v_mfma_f32_16x16x32_f16 v[78:81], v[146:149], v[230:233], v[78:81]
	v_mfma_f32_16x16x32_f16 v[70:73], v[154:157], v[230:233], v[70:73]
	v_mfma_f32_16x16x32_f16 v[126:129], v[150:153], v[182:185], v[126:129]
	v_mfma_f32_16x16x32_f16 v[118:121], v[158:161], v[182:185], v[118:121]
	v_mfma_f32_16x16x32_f16 v[110:113], v[150:153], v[192:195], v[110:113]
	v_mfma_f32_16x16x32_f16 v[102:105], v[158:161], v[192:195], v[102:105]
	v_mfma_f32_16x16x32_f16 v[94:97], v[150:153], v[200:203], v[94:97]
	v_mfma_f32_16x16x32_f16 v[86:89], v[158:161], v[200:203], v[86:89]
	v_mfma_f32_16x16x32_f16 v[78:81], v[150:153], v[234:237], v[78:81]
	v_mfma_f32_16x16x32_f16 v[70:73], v[158:161], v[234:237], v[70:73]
	s_setprio 0
	s_setprio 1
	v_mfma_f32_16x16x32_f16 v[122:125], v[162:165], v[178:181], v[122:125]
	v_mfma_f32_16x16x32_f16 v[114:117], v[170:173], v[178:181], v[114:117]
	v_mfma_f32_16x16x32_f16 v[106:109], v[162:165], v[186:189], v[106:109]
	v_mfma_f32_16x16x32_f16 v[98:101], v[170:173], v[186:189], v[98:101]
	v_mfma_f32_16x16x32_f16 v[90:93], v[162:165], v[196:199], v[90:93]
	v_mfma_f32_16x16x32_f16 v[82:85], v[170:173], v[196:199], v[82:85]
	v_mfma_f32_16x16x32_f16 v[74:77], v[162:165], v[230:233], v[74:77]
	v_mfma_f32_16x16x32_f16 v[66:69], v[170:173], v[230:233], v[66:69]
	v_mfma_f32_16x16x32_f16 v[122:125], v[166:169], v[182:185], v[122:125]
	v_mfma_f32_16x16x32_f16 v[114:117], v[174:177], v[182:185], v[114:117]
	v_mfma_f32_16x16x32_f16 v[106:109], v[166:169], v[192:195], v[106:109]
	v_mfma_f32_16x16x32_f16 v[98:101], v[174:177], v[192:195], v[98:101]
	v_mfma_f32_16x16x32_f16 v[90:93], v[166:169], v[200:203], v[90:93]
	v_mfma_f32_16x16x32_f16 v[82:85], v[174:177], v[200:203], v[82:85]
	v_mfma_f32_16x16x32_f16 v[74:77], v[166:169], v[234:237], v[74:77]
	v_mfma_f32_16x16x32_f16 v[66:69], v[174:177], v[234:237], v[66:69]
	s_setprio 0
	s_barrier
	s_add_i32 s63, s63, s44
	v_lshl_add_u64 v[218:219], s[34:35], 0, v[132:133]
	s_mov_b32 m0, s63
	ds_read_b128 v[178:181], v144 offset:16384
	ds_read_b128 v[182:185], v144 offset:17408
	ds_read_b128 v[186:189], v144 offset:18432
	ds_read_b128 v[192:195], v144 offset:19456
	ds_read_b128 v[196:199], v144 offset:20480
	ds_read_b128 v[200:203], v144 offset:21504
	ds_read_b128 v[230:233], v144 offset:22528
	ds_read_b128 v[234:237], v144 offset:23552
	global_load_lds_dwordx4 v[218:219], off
	s_add_i32 m0, s63, 0x2000
	s_add_u32 s64, s34, 0x40000
	v_lshl_add_u64 v[220:221], s[34:35], 0, v[136:137]
	s_addc_u32 s65, s35, 0
	s_add_i32 s63, s66, s44
	global_load_lds_dwordx4 v[220:221], off
	v_lshl_add_u64 v[222:223], s[64:65], 0, v[132:133]
	s_mov_b32 m0, s63
	v_lshl_add_u64 v[224:225], s[40:41], 0, v[134:135]
	global_load_lds_dwordx4 v[222:223], off
	v_lshl_add_u64 v[222:223], s[64:65], 0, v[136:137]
	s_add_i32 m0, s63, 0x2000
	s_nop 0
	global_load_lds_dwordx4 v[222:223], off
	v_lshl_add_u64 v[222:223], s[40:41], 0, v[130:131]
	s_mov_b32 m0, s45
	s_nop 0
	global_load_lds_dwordx4 v[222:223], off
	s_mov_b32 m0, s47
	s_nop 0
	global_load_lds_dwordx4 v[224:225], off
	s_waitcnt vmcnt(8)
	s_waitcnt lgkmcnt(0)
	s_barrier
	s_setprio 1
	s_waitcnt lgkmcnt(0)
	v_mfma_f32_16x16x32_f16 v[62:65], v[146:149], v[178:181], v[62:65]
	v_mfma_f32_16x16x32_f16 v[54:57], v[154:157], v[178:181], v[54:57]
	v_mfma_f32_16x16x32_f16 v[46:49], v[146:149], v[186:189], v[46:49]
	v_mfma_f32_16x16x32_f16 v[38:41], v[154:157], v[186:189], v[38:41]
	v_mfma_f32_16x16x32_f16 v[30:33], v[146:149], v[196:199], v[30:33]
	v_mfma_f32_16x16x32_f16 v[22:25], v[154:157], v[196:199], v[22:25]
	v_mfma_f32_16x16x32_f16 v[14:17], v[146:149], v[230:233], v[14:17]
	v_mfma_f32_16x16x32_f16 v[6:9], v[154:157], v[230:233], v[6:9]
	v_mfma_f32_16x16x32_f16 v[62:65], v[150:153], v[182:185], v[62:65]
	v_mfma_f32_16x16x32_f16 v[54:57], v[158:161], v[182:185], v[54:57]
	v_mfma_f32_16x16x32_f16 v[46:49], v[150:153], v[192:195], v[46:49]
	v_mfma_f32_16x16x32_f16 v[38:41], v[158:161], v[192:195], v[38:41]
	v_mfma_f32_16x16x32_f16 v[30:33], v[150:153], v[200:203], v[30:33]
	v_mfma_f32_16x16x32_f16 v[22:25], v[158:161], v[200:203], v[22:25]
	v_mfma_f32_16x16x32_f16 v[14:17], v[150:153], v[234:237], v[14:17]
	v_mfma_f32_16x16x32_f16 v[6:9], v[158:161], v[234:237], v[6:9]
	s_setprio 0
	s_setprio 1
	v_mfma_f32_16x16x32_f16 v[58:61], v[162:165], v[178:181], v[58:61]
	v_mfma_f32_16x16x32_f16 v[50:53], v[170:173], v[178:181], v[50:53]
	v_mfma_f32_16x16x32_f16 v[42:45], v[162:165], v[186:189], v[42:45]
	v_mfma_f32_16x16x32_f16 v[34:37], v[170:173], v[186:189], v[34:37]
	v_mfma_f32_16x16x32_f16 v[26:29], v[162:165], v[196:199], v[26:29]
	v_mfma_f32_16x16x32_f16 v[18:21], v[170:173], v[196:199], v[18:21]
	v_mfma_f32_16x16x32_f16 v[10:13], v[162:165], v[230:233], v[10:13]
	v_mfma_f32_16x16x32_f16 v[2:5], v[170:173], v[230:233], v[2:5]
	v_mfma_f32_16x16x32_f16 v[58:61], v[166:169], v[182:185], v[58:61]
	v_mfma_f32_16x16x32_f16 v[50:53], v[174:177], v[182:185], v[50:53]
	v_mfma_f32_16x16x32_f16 v[42:45], v[166:169], v[192:195], v[42:45]
	v_mfma_f32_16x16x32_f16 v[34:37], v[174:177], v[192:195], v[34:37]
	v_mfma_f32_16x16x32_f16 v[26:29], v[166:169], v[200:203], v[26:29]
	v_mfma_f32_16x16x32_f16 v[18:21], v[174:177], v[200:203], v[18:21]
	v_mfma_f32_16x16x32_f16 v[10:13], v[166:169], v[234:237], v[10:13]
	v_mfma_f32_16x16x32_f16 v[2:5], v[174:177], v[234:237], v[2:5]
	s_setprio 0
	s_barrier
; #define PG8_STAGE(bufoff, gbase, voff) do { _Pragma("unroll") for (int _i = 0; _i < 2; ++_i) \
;         __builtin_amdgcn_global_load_lds((const unsigned*)((const char*)(gbase) + (voff)[_i]), (PG8_LAS unsigned*)(lds + (bufoff) + ldsw + _i * 8192), 16, 0, 0); } while (0)
; #define PG8_LDA(dst, b, h) do { _Pragma("unroll") for (int m = 0; m < 4; ++m) _Pragma("unroll") for (int k = 0; k < 2; ++k) dst[m][k] = *(const PG8_LAS bf16x8*)(lds + PG8_SA(b, h) + aoff + m * 2048 + k * 1024); } while (0)
; #define PG8_LDB(dst, b, h) do { _Pragma("unroll") for (int n = 0; n < 2; ++n) _Pragma("unroll") for (int k = 0; k < 2; ++k) dst[n][k] = *(const PG8_LAS bf16x8*)(lds + PG8_SB(b, h) + boff + n * 2048 + k * 1024); } while (0)
; #define PG8_WAIT_V(n) asm volatile("s_waitcnt vmcnt(" #n ")" ::: "memory")
; #define PG8_WAIT_L(n) asm volatile("s_waitcnt lgkmcnt(" #n ")" ::: "memory")
; #define PG8_BAR __builtin_amdgcn_s_barrier()
; #define PG8_SCHED __builtin_amdgcn_sched_barrier(0)
; template <class Epi, class Sched, bool ALIGN_EPI = false, bool SP2 = false>
; __device__ __forceinline__ void gemm_phase(PG8_LAS unsigned char* lds, const Gemm g, const Sched& S, const Epi& E, const int tid_in) {
;     ...
;             PG8_LDB(B0, 1, 0); PG8_LDB(B1, 1, 1); PG8_SCHED; PG8_LDA(At, 1, 0); PG8_STAGE(PG8_SA(0, 1), a2 + hstep, voffA);
;             PG8_WAIT_V(8); PG8_WAIT_L(0); PG8_BAR; PG8_MMA(0, 0, At, B0); PG8_MMA(0, 1, At, B1); PG8_BAR; PG8_SCHED;
.Lmid_104:
	s_add_i32 s63, 0, 0x18000
	v_add_u32_e32 v145, s63, v143
	s_add_i32 s64, 0, 0x1c000
	ds_read_b128 v[146:149], v145
	ds_read_b128 v[150:153], v145 offset:1024
	ds_read_b128 v[154:157], v145 offset:2048
	ds_read_b128 v[158:161], v145 offset:3072
	v_add_u32_e32 v145, s64, v143
	ds_read_b128 v[162:165], v145
	ds_read_b128 v[166:169], v145 offset:1024
	ds_read_b128 v[170:173], v145 offset:2048
	ds_read_b128 v[174:177], v145 offset:3072
	s_add_u32 s40, s40, 0x40000
	s_addc_u32 s41, s41, 0
	s_mov_b32 m0, s48
	v_lshl_add_u64 v[238:239], s[40:41], 0, v[130:131]
	ds_read_b128 v[178:181], v144 offset:32768
	ds_read_b128 v[182:185], v144 offset:33792
	ds_read_b128 v[186:189], v144 offset:34816
	ds_read_b128 v[192:195], v144 offset:35840
	ds_read_b128 v[196:199], v144 offset:36864
	ds_read_b128 v[200:203], v144 offset:37888
	ds_read_b128 v[230:233], v144 offset:38912
	ds_read_b128 v[234:237], v144 offset:39936
	global_load_lds_dwordx4 v[238:239], off
	v_lshl_add_u64 v[238:239], s[40:41], 0, v[134:135]
	s_mov_b32 m0, s49
	s_nop 0
	global_load_lds_dwordx4 v[238:239], off
	s_waitcnt vmcnt(8)
	s_waitcnt lgkmcnt(0)
	s_barrier
	s_setprio 1
	s_waitcnt lgkmcnt(0)
	v_mfma_f32_16x16x32_f16 v[126:129], v[146:149], v[178:181], v[126:129]
	v_mfma_f32_16x16x32_f16 v[118:121], v[154:157], v[178:181], v[118:121]
	v_mfma_f32_16x16x32_f16 v[110:113], v[146:149], v[186:189], v[110:113]
	v_mfma_f32_16x16x32_f16 v[102:105], v[154:157], v[186:189], v[102:105]
	v_mfma_f32_16x16x32_f16 v[94:97], v[146:149], v[196:199], v[94:97]
	v_mfma_f32_16x16x32_f16 v[86:89], v[154:157], v[196:199], v[86:89]
	v_mfma_f32_16x16x32_f16 v[78:81], v[146:149], v[230:233], v[78:81]
	v_mfma_f32_16x16x32_f16 v[70:73], v[154:157], v[230:233], v[70:73]
	v_mfma_f32_16x16x32_f16 v[126:129], v[150:153], v[182:185], v[126:129]
	v_mfma_f32_16x16x32_f16 v[118:121], v[158:161], v[182:185], v[118:121]
	v_mfma_f32_16x16x32_f16 v[110:113], v[150:153], v[192:195], v[110:113]
	v_mfma_f32_16x16x32_f16 v[102:105], v[158:161], v[192:195], v[102:105]
	v_mfma_f32_16x16x32_f16 v[94:97], v[150:153], v[200:203], v[94:97]
	v_mfma_f32_16x16x32_f16 v[86:89], v[158:161], v[200:203], v[86:89]
	v_mfma_f32_16x16x32_f16 v[78:81], v[150:153], v[234:237], v[78:81]
	v_mfma_f32_16x16x32_f16 v[70:73], v[158:161], v[234:237], v[70:73]
	s_setprio 0
	s_setprio 1
	v_mfma_f32_16x16x32_f16 v[122:125], v[162:165], v[178:181], v[122:125]
	v_mfma_f32_16x16x32_f16 v[114:117], v[170:173], v[178:181], v[114:117]
	v_mfma_f32_16x16x32_f16 v[106:109], v[162:165], v[186:189], v[106:109]
	v_mfma_f32_16x16x32_f16 v[98:101], v[170:173], v[186:189], v[98:101]
	v_mfma_f32_16x16x32_f16 v[90:93], v[162:165], v[196:199], v[90:93]
	v_mfma_f32_16x16x32_f16 v[82:85], v[170:173], v[196:199], v[82:85]
	v_mfma_f32_16x16x32_f16 v[74:77], v[162:165], v[230:233], v[74:77]
	v_mfma_f32_16x16x32_f16 v[66:69], v[170:173], v[230:233], v[66:69]
	v_mfma_f32_16x16x32_f16 v[122:125], v[166:169], v[182:185], v[122:125]
	v_mfma_f32_16x16x32_f16 v[114:117], v[174:177], v[182:185], v[114:117]
	v_mfma_f32_16x16x32_f16 v[106:109], v[166:169], v[192:195], v[106:109]
	v_mfma_f32_16x16x32_f16 v[98:101], v[174:177], v[192:195], v[98:101]
	v_mfma_f32_16x16x32_f16 v[90:93], v[166:169], v[200:203], v[90:93]
	v_mfma_f32_16x16x32_f16 v[82:85], v[174:177], v[200:203], v[82:85]
	v_mfma_f32_16x16x32_f16 v[74:77], v[166:169], v[234:237], v[74:77]
	v_mfma_f32_16x16x32_f16 v[66:69], v[174:177], v[234:237], v[66:69]
	s_setprio 0
	s_barrier
; #define PG8_STAGE(bufoff, gbase, voff) do { _Pragma("unroll") for (int _i = 0; _i < 2; ++_i) \
;         __builtin_amdgcn_global_load_lds((const unsigned*)((const char*)(gbase) + (voff)[_i]), (PG8_LAS unsigned*)(lds + (bufoff) + ldsw + _i * 8192), 16, 0, 0); } while (0)
; #define PG8_LDA(dst, b, h) do { _Pragma("unroll") for (int m = 0; m < 4; ++m) _Pragma("unroll") for (int k = 0; k < 2; ++k) dst[m][k] = *(const PG8_LAS bf16x8*)(lds + PG8_SA(b, h) + aoff + m * 2048 + k * 1024); } while (0)
; #define PG8_WAIT_V(n) asm volatile("s_waitcnt vmcnt(" #n ")" ::: "memory")
; #define PG8_WAIT_L(n) asm volatile("s_waitcnt lgkmcnt(" #n ")" ::: "memory")
; #define PG8_BAR __builtin_amdgcn_s_barrier()
; #define PG8_SCHED __builtin_amdgcn_sched_barrier(0)
; template <class Epi, class Sched, bool ALIGN_EPI = false, bool SP2 = false>
; __device__ __forceinline__ void gemm_phase(PG8_LAS unsigned char* lds, const Gemm g, const Sched& S, const Epi& E, const int tid_in) {
;     ...
;         for (int t = 0; t < nt; t += 2) {
;             const bool last = (t == nt - 2);
;             const char* a1 = cA + (size_t)(t + 1) * kstep;
;             const char* a2 = last ? nA : cA + (size_t)(t + 2) * kstep; const char* b2 = last ? nB : cB + (size_t)(t + 2) * kstep;
;     ...
;             PG8_LDA(At, 1, 1); PG8_STAGE(PG8_SB(1, 0), b3, voffB); PG8_STAGE(PG8_SB(1, 1), b3 + hstep, voffB); PG8_STAGE(PG8_SA(1, 0), a3, voffA);
;             PG8_WAIT_V(8); PG8_WAIT_L(0); PG8_BAR; PG8_MMA(1, 0, At, B0); PG8_MMA(1, 1, At, B1); PG8_BAR; PG8_SCHED;
	s_add_i32 s40, s63, s44
	v_lshl_add_u64 v[218:219], v[218:219], 0, s[24:25]
	s_mov_b32 m0, s40
	ds_read_b128 v[178:181], v144 offset:49152
	ds_read_b128 v[182:185], v144 offset:50176
	ds_read_b128 v[186:189], v144 offset:51200
	ds_read_b128 v[192:195], v144 offset:52224
	ds_read_b128 v[196:199], v144 offset:53248
	ds_read_b128 v[200:203], v144 offset:54272
	ds_read_b128 v[230:233], v144 offset:55296
	ds_read_b128 v[234:237], v144 offset:56320
	global_load_lds_dwordx4 v[218:219], off
	s_add_i32 m0, s40, 0x2000
	s_add_u32 s34, s34, 0x40080
	v_lshl_add_u64 v[218:219], v[220:221], 0, s[24:25]
	s_addc_u32 s35, s35, 0
	s_add_i32 s40, s64, s44
	global_load_lds_dwordx4 v[218:219], off
	v_lshl_add_u64 v[218:219], s[34:35], 0, v[132:133]
	s_mov_b32 m0, s40
	s_nop 0
	global_load_lds_dwordx4 v[218:219], off
	v_lshl_add_u64 v[218:219], s[34:35], 0, v[136:137]
	s_add_i32 m0, s40, 0x2000
	s_nop 0
	global_load_lds_dwordx4 v[218:219], off
	v_lshl_add_u64 v[218:219], v[222:223], 0, s[24:25]
	s_mov_b32 m0, s52
	s_nop 0
	global_load_lds_dwordx4 v[218:219], off
	v_lshl_add_u64 v[218:219], v[224:225], 0, s[24:25]
	s_mov_b32 m0, s53
	s_nop 0
	global_load_lds_dwordx4 v[218:219], off
	s_waitcnt vmcnt(8)
	s_waitcnt lgkmcnt(0)
	s_barrier
	s_setprio 1
	s_waitcnt lgkmcnt(0)
	v_mfma_f32_16x16x32_f16 v[62:65], v[146:149], v[178:181], v[62:65]
	v_mfma_f32_16x16x32_f16 v[54:57], v[154:157], v[178:181], v[54:57]
	v_mfma_f32_16x16x32_f16 v[46:49], v[146:149], v[186:189], v[46:49]
	v_mfma_f32_16x16x32_f16 v[38:41], v[154:157], v[186:189], v[38:41]
	v_mfma_f32_16x16x32_f16 v[30:33], v[146:149], v[196:199], v[30:33]
	v_mfma_f32_16x16x32_f16 v[22:25], v[154:157], v[196:199], v[22:25]
	v_mfma_f32_16x16x32_f16 v[14:17], v[146:149], v[230:233], v[14:17]
	v_mfma_f32_16x16x32_f16 v[6:9], v[154:157], v[230:233], v[6:9]
	v_mfma_f32_16x16x32_f16 v[62:65], v[150:153], v[182:185], v[62:65]
	v_mfma_f32_16x16x32_f16 v[54:57], v[158:161], v[182:185], v[54:57]
	v_mfma_f32_16x16x32_f16 v[46:49], v[150:153], v[192:195], v[46:49]
	v_mfma_f32_16x16x32_f16 v[38:41], v[158:161], v[192:195], v[38:41]
	v_mfma_f32_16x16x32_f16 v[30:33], v[150:153], v[200:203], v[30:33]
	v_mfma_f32_16x16x32_f16 v[22:25], v[158:161], v[200:203], v[22:25]
	v_mfma_f32_16x16x32_f16 v[14:17], v[150:153], v[234:237], v[14:17]
	v_mfma_f32_16x16x32_f16 v[6:9], v[158:161], v[234:237], v[6:9]
	s_setprio 0
	s_setprio 1
	v_mfma_f32_16x16x32_f16 v[58:61], v[162:165], v[178:181], v[58:61]
	v_mfma_f32_16x16x32_f16 v[50:53], v[170:173], v[178:181], v[50:53]
	v_mfma_f32_16x16x32_f16 v[42:45], v[162:165], v[186:189], v[42:45]
	v_mfma_f32_16x16x32_f16 v[34:37], v[170:173], v[186:189], v[34:37]
	v_mfma_f32_16x16x32_f16 v[26:29], v[162:165], v[196:199], v[26:29]
	v_mfma_f32_16x16x32_f16 v[18:21], v[170:173], v[196:199], v[18:21]
	v_mfma_f32_16x16x32_f16 v[10:13], v[162:165], v[230:233], v[10:13]
	v_mfma_f32_16x16x32_f16 v[2:5], v[170:173], v[230:233], v[2:5]
	v_mfma_f32_16x16x32_f16 v[58:61], v[166:169], v[182:185], v[58:61]
	v_mfma_f32_16x16x32_f16 v[50:53], v[174:177], v[182:185], v[50:53]
	v_mfma_f32_16x16x32_f16 v[42:45], v[166:169], v[192:195], v[42:45]
	v_mfma_f32_16x16x32_f16 v[34:37], v[174:177], v[192:195], v[34:37]
	v_mfma_f32_16x16x32_f16 v[26:29], v[166:169], v[200:203], v[26:29]
	v_mfma_f32_16x16x32_f16 v[18:21], v[174:177], v[200:203], v[18:21]
	v_mfma_f32_16x16x32_f16 v[10:13], v[166:169], v[234:237], v[10:13]
	v_mfma_f32_16x16x32_f16 v[2:5], v[174:177], v[234:237], v[2:5]
	s_setprio 0
	s_barrier
	s_add_u32 s28, s28, 0x100
	s_addc_u32 s29, s29, 0
	s_add_u32 s60, s60, 0x100
	s_addc_u32 s61, s61, 0
	s_cmp_ge_i32 s62, s16
	s_mov_b32 s34, s62
	s_cbranch_scc0 .LBB0_104
	s_mov_b64 s[60:61], 0x800
	v_readlane_b32 s62, v254, 52
	v_readlane_b32 s63, v254, 53
	s_and_b64 vcc, exec, s[14:15]
	s_cbranch_vccz .LBB0_107

; __device__ __forceinline__ float sigmoidf_(float x) { return __builtin_amdgcn_rcpf(1.f + __expf(-x)); }
;     __device__ __forceinline__ void operator()(const pg8::f32x4 (&acc)[2][2][4][2], const pg8::Unit& uu, int wr, int wc, int fr, int fq) const {
;         asm volatile("" : "+v"(fr), "+v"(fq));
;         const int upm = uu.pm & 0xffff, upn = uu.pn & 0xffff, unt = uu.pm >> 16; (void)unt;
;         const int row0 = upm * 256 + wr * 64 + fr, col = upn * 128 + wc * 32 + 8 * fq;
; #pragma unroll
;         for (int ai = 0; ai < 2; ++ai)
; #pragma unroll
;             for (int m = 0; m < 4; ++m) { float o[8];
; #pragma unroll
;                 for (int n = 0; n < 2; ++n)
; #pragma unroll
;                     for (int e = 0; e < 4; ++e) { const float g = acc[ai][0][m][n][e], up = acc[ai][1][m][n][e]; o[4 * n + e] = g * sigmoidf_(g) * up; }
;                 u32x4 w; w.x = pg8::cvt_pk_bf16(o[0], o[1]); w.y = pg8::cvt_pk_bf16(o[2], o[3]); w.z = pg8::cvt_pk_bf16(o[4], o[5]); w.w = pg8::cvt_pk_bf16(o[6], o[7]);
;                 *(u32x4*)(O + (size_t)(row0 + ai * 128 + m * 16) * DFF + col) = w; }
.LBB0_107:
	v_mul_f32_e32 v147, 0xbfb8aa3b, v126
	v_exp_f32_e32 v148, v147
	v_mul_f32_e32 v147, 0xbfb8aa3b, v127
	v_exp_f32_e32 v149, v147
	v_mul_f32_e32 v150, 0xbfb8aa3b, v128
	v_mul_f32_e32 v151, 0xbfb8aa3b, v129
	v_mul_f32_e32 v152, 0xbfb8aa3b, v118
	v_mul_f32_e32 v153, 0xbfb8aa3b, v119
	v_exp_f32_e32 v150, v150
	v_exp_f32_e32 v151, v151
	v_exp_f32_e32 v152, v152
	v_exp_f32_e32 v153, v153
	v_mul_f32_e32 v154, 0xbfb8aa3b, v120
	v_mul_f32_e32 v155, 0xbfb8aa3b, v121
	v_exp_f32_e32 v154, v154
	v_exp_f32_e32 v155, v155
	v_add_f32_e32 v148, 1.0, v148
	v_add_f32_e32 v149, 1.0, v149
	v_rcp_f32_e32 v148, v148
	v_rcp_f32_e32 v149, v149
	v_add_f32_e32 v150, 1.0, v150
	v_add_f32_e32 v151, 1.0, v151
	v_add_f32_e32 v152, 1.0, v152
	v_add_f32_e32 v153, 1.0, v153
	v_rcp_f32_e32 v150, v150
	v_rcp_f32_e32 v151, v151
	v_rcp_f32_e32 v152, v152
	v_rcp_f32_e32 v153, v153
	v_add_f32_e32 v154, 1.0, v154
	v_add_f32_e32 v155, 1.0, v155
	v_rcp_f32_e32 v154, v154
	v_rcp_f32_e32 v155, v155
	v_pk_mul_f32 v[126:127], v[126:127], v[148:149]
	s_lshl_b32 s28, s57, 7
	v_pk_mul_f32 v[122:123], v[122:123], v[126:127]
	v_pk_mul_f32 v[126:127], v[128:129], v[150:151]
	v_pk_mul_f32 v[118:119], v[118:119], v[152:153]
	v_mov_b32_e32 v145, v1
	v_mov_b32_e32 v146, v142
	s_lshl_b32 s16, s58, 8
	s_and_b32 s28, s28, 0x7fff80
	v_pk_mul_f32 v[124:125], v[124:125], v[126:127]
	v_pk_mul_f32 v[114:115], v[114:115], v[118:119]
	s_and_b32 s16, s16, 0xffff00
	s_or_b32 s28, s28, s51
	v_cvt_pk_f16_f32 v122, v122, v123
	v_cvt_pk_f16_f32 v123, v124, v125
	v_cvt_pk_f16_f32 v124, v114, v115
	v_pk_mul_f32 v[114:115], v[120:121], v[154:155]
	v_mul_f32_e32 v120, 0xbfb8aa3b, v110
	v_mul_f32_e32 v121, 0xbfb8aa3b, v111
	v_lshl_add_u32 v146, v146, 3, s28
	s_add_i32 s16, s16, s50
	v_pk_mul_f32 v[114:115], v[116:117], v[114:115]
	v_exp_f32_e32 v120, v120
	v_exp_f32_e32 v121, v121
	v_add_u32_e32 v145, s16, v145
	v_ashrrev_i32_e32 v147, 31, v146
	v_cvt_pk_f16_f32 v125, v114, v115
	v_mov_b64_e32 v[114:115], s[2:3]
	v_mad_i64_i32 v[118:119], s[28:29], v145, s81, v[114:115]
	v_lshlrev_b64 v[116:117], 1, v[146:147]
	v_lshl_add_u64 v[118:119], v[118:119], 0, v[116:117]
	global_store_dwordx4 v[118:119], v[122:125], off
	v_add_f32_e32 v118, 1.0, v120
	v_add_f32_e32 v119, 1.0, v121
	v_mul_f32_e32 v120, 0xbfb8aa3b, v112
	v_mul_f32_e32 v121, 0xbfb8aa3b, v113
	v_mul_f32_e32 v122, 0xbfb8aa3b, v102
	v_mul_f32_e32 v123, 0xbfb8aa3b, v103
	v_exp_f32_e32 v120, v120
	v_exp_f32_e32 v121, v121
	v_exp_f32_e32 v122, v122
	v_exp_f32_e32 v123, v123
	v_mul_f32_e32 v124, 0xbfb8aa3b, v104
	v_mul_f32_e32 v125, 0xbfb8aa3b, v105
	v_exp_f32_e32 v124, v124
	v_exp_f32_e32 v125, v125
	v_rcp_f32_e32 v118, v118
	v_rcp_f32_e32 v119, v119
	v_add_f32_e32 v120, 1.0, v120
	v_add_f32_e32 v121, 1.0, v121
	v_add_f32_e32 v122, 1.0, v122
	v_add_f32_e32 v123, 1.0, v123
	v_rcp_f32_e32 v120, v120
	v_rcp_f32_e32 v121, v121
	v_rcp_f32_e32 v122, v122
	v_rcp_f32_e32 v123, v123
	v_add_f32_e32 v124, 1.0, v124
	v_add_f32_e32 v125, 1.0, v125
	v_rcp_f32_e32 v124, v124
	v_rcp_f32_e32 v125, v125
	v_pk_mul_f32 v[110:111], v[110:111], v[118:119]
	v_pk_mul_f32 v[102:103], v[102:103], v[122:123]
	v_pk_mul_f32 v[106:107], v[106:107], v[110:111]
	v_pk_mul_f32 v[110:111], v[112:113], v[120:121]
	v_pk_mul_f32 v[98:99], v[98:99], v[102:103]
	v_pk_mul_f32 v[108:109], v[108:109], v[110:111]
	v_cvt_pk_f16_f32 v106, v106, v107
	v_cvt_pk_f16_f32 v107, v108, v109
	v_cvt_pk_f16_f32 v108, v98, v99
	v_pk_mul_f32 v[98:99], v[104:105], v[124:125]
	v_mul_f32_e32 v102, 0xbfb8aa3b, v86
	v_pk_mul_f32 v[98:99], v[100:101], v[98:99]
	v_mul_f32_e32 v100, 0xbfb8aa3b, v94
	v_mul_f32_e32 v101, 0xbfb8aa3b, v95
	v_exp_f32_e32 v100, v100
	v_exp_f32_e32 v101, v101
	v_cvt_pk_f16_f32 v109, v98, v99
	v_add_u32_e32 v98, 16, v145
	v_mad_i64_i32 v[98:99], s[28:29], v98, s81, v[114:115]
	v_lshl_add_u64 v[98:99], v[98:99], 0, v[116:117]
	global_store_dwordx4 v[98:99], v[106:109], off
	v_add_f32_e32 v98, 1.0, v100
	v_add_f32_e32 v99, 1.0, v101
	v_mul_f32_e32 v100, 0xbfb8aa3b, v96
	v_mul_f32_e32 v101, 0xbfb8aa3b, v97
	v_mul_f32_e32 v103, 0xbfb8aa3b, v87
	v_exp_f32_e32 v100, v100
	v_exp_f32_e32 v101, v101
	v_exp_f32_e32 v102, v102
	v_exp_f32_e32 v103, v103
	v_mul_f32_e32 v104, 0xbfb8aa3b, v88
	v_mul_f32_e32 v105, 0xbfb8aa3b, v89
	v_exp_f32_e32 v104, v104
	v_exp_f32_e32 v105, v105
	v_rcp_f32_e32 v98, v98
	v_rcp_f32_e32 v99, v99
	v_add_f32_e32 v100, 1.0, v100
	v_add_f32_e32 v101, 1.0, v101
	v_add_f32_e32 v102, 1.0, v102
	v_add_f32_e32 v103, 1.0, v103
	v_rcp_f32_e32 v100, v100
	v_rcp_f32_e32 v101, v101
	v_rcp_f32_e32 v102, v102
	v_rcp_f32_e32 v103, v103
	v_add_f32_e32 v104, 1.0, v104
	v_add_f32_e32 v105, 1.0, v105
	v_rcp_f32_e32 v104, v104
	v_rcp_f32_e32 v105, v105
	v_pk_mul_f32 v[94:95], v[94:95], v[98:99]
	v_pk_mul_f32 v[86:87], v[86:87], v[102:103]
	v_pk_mul_f32 v[90:91], v[90:91], v[94:95]
	v_pk_mul_f32 v[94:95], v[96:97], v[100:101]
	v_pk_mul_f32 v[82:83], v[82:83], v[86:87]
	v_pk_mul_f32 v[92:93], v[92:93], v[94:95]
	v_cvt_pk_f16_f32 v90, v90, v91
	v_cvt_pk_f16_f32 v91, v92, v93
	v_cvt_pk_f16_f32 v92, v82, v83
	v_pk_mul_f32 v[82:83], v[88:89], v[104:105]
	v_mul_f32_e32 v86, 0xbfb8aa3b, v70
	v_pk_mul_f32 v[82:83], v[84:85], v[82:83]
	v_mul_f32_e32 v84, 0xbfb8aa3b, v78
	v_mul_f32_e32 v85, 0xbfb8aa3b, v79
	v_exp_f32_e32 v84, v84
	v_exp_f32_e32 v85, v85
	v_cvt_pk_f16_f32 v93, v82, v83
	v_add_u32_e32 v82, 32, v145
	v_mad_i64_i32 v[82:83], s[28:29], v82, s81, v[114:115]
	v_lshl_add_u64 v[82:83], v[82:83], 0, v[116:117]
	global_store_dwordx4 v[82:83], v[90:93], off
	v_add_f32_e32 v82, 1.0, v84
	v_add_f32_e32 v83, 1.0, v85
	v_mul_f32_e32 v84, 0xbfb8aa3b, v80
	v_mul_f32_e32 v85, 0xbfb8aa3b, v81
; __device__ __forceinline__ float sigmoidf_(float x) { return __builtin_amdgcn_rcpf(1.f + __expf(-x)); }
;     __device__ __forceinline__ void operator()(const pg8::f32x4 (&acc)[2][2][4][2], const pg8::Unit& uu, int wr, int wc, int fr, int fq) const {
;     ...
;             for (int m = 0; m < 4; ++m) { float o[8];
; #pragma unroll
;                 for (int n = 0; n < 2; ++n)
; #pragma unroll
;                     for (int e = 0; e < 4; ++e) { const float g = acc[ai][0][m][n][e], up = acc[ai][1][m][n][e]; o[4 * n + e] = g * sigmoidf_(g) * up; }
;                 u32x4 w; w.x = pg8::cvt_pk_bf16(o[0], o[1]); w.y = pg8::cvt_pk_bf16(o[2], o[3]); w.z = pg8::cvt_pk_bf16(o[4], o[5]); w.w = pg8::cvt_pk_bf16(o[6], o[7]);
;                 *(u32x4*)(O + (size_t)(row0 + ai * 128 + m * 16) * DFF + col) = w; }
	v_mul_f32_e32 v87, 0xbfb8aa3b, v71
	v_exp_f32_e32 v84, v84
	v_exp_f32_e32 v85, v85
	v_exp_f32_e32 v86, v86
	v_exp_f32_e32 v87, v87
	v_mul_f32_e32 v88, 0xbfb8aa3b, v72
	v_mul_f32_e32 v89, 0xbfb8aa3b, v73
	v_exp_f32_e32 v88, v88
	v_exp_f32_e32 v89, v89
	v_rcp_f32_e32 v82, v82
	v_rcp_f32_e32 v83, v83
	v_add_f32_e32 v84, 1.0, v84
	v_add_f32_e32 v85, 1.0, v85
	v_add_f32_e32 v86, 1.0, v86
	v_add_f32_e32 v87, 1.0, v87
	v_rcp_f32_e32 v84, v84
	v_rcp_f32_e32 v85, v85
	v_rcp_f32_e32 v86, v86
	v_rcp_f32_e32 v87, v87
	v_add_f32_e32 v88, 1.0, v88
	v_add_f32_e32 v89, 1.0, v89
	v_rcp_f32_e32 v88, v88
	v_rcp_f32_e32 v89, v89
	v_pk_mul_f32 v[78:79], v[78:79], v[82:83]
	v_pk_mul_f32 v[70:71], v[70:71], v[86:87]
	v_pk_mul_f32 v[74:75], v[74:75], v[78:79]
	v_pk_mul_f32 v[78:79], v[80:81], v[84:85]
	v_pk_mul_f32 v[66:67], v[66:67], v[70:71]
	v_pk_mul_f32 v[76:77], v[76:77], v[78:79]
	v_cvt_pk_f16_f32 v74, v74, v75
	v_cvt_pk_f16_f32 v75, v76, v77
	v_cvt_pk_f16_f32 v76, v66, v67
	v_pk_mul_f32 v[66:67], v[72:73], v[88:89]
	v_mul_f32_e32 v70, 0xbfb8aa3b, v54
	v_pk_mul_f32 v[66:67], v[68:69], v[66:67]
	v_mul_f32_e32 v68, 0xbfb8aa3b, v64
	v_cvt_pk_f16_f32 v77, v66, v67
	v_add_u32_e32 v66, 48, v145
	v_mad_i64_i32 v[66:67], s[28:29], v66, s81, v[114:115]
	v_lshl_add_u64 v[66:67], v[66:67], 0, v[116:117]
	global_store_dwordx4 v[66:67], v[74:77], off
	v_mul_f32_e32 v66, 0xbfb8aa3b, v62
	v_mul_f32_e32 v67, 0xbfb8aa3b, v63
	v_exp_f32_e32 v66, v66
	v_exp_f32_e32 v67, v67
	v_mul_f32_e32 v69, 0xbfb8aa3b, v65
	v_mul_f32_e32 v71, 0xbfb8aa3b, v55
	v_exp_f32_e32 v68, v68
	v_exp_f32_e32 v69, v69
	v_exp_f32_e32 v70, v70
	v_exp_f32_e32 v71, v71
	v_mul_f32_e32 v72, 0xbfb8aa3b, v56
	v_mul_f32_e32 v73, 0xbfb8aa3b, v57
	v_exp_f32_e32 v72, v72
	v_exp_f32_e32 v73, v73
	v_add_f32_e32 v66, 1.0, v66
	v_add_f32_e32 v67, 1.0, v67
	v_rcp_f32_e32 v66, v66
	v_rcp_f32_e32 v67, v67
	v_add_f32_e32 v68, 1.0, v68
	v_add_f32_e32 v69, 1.0, v69
	v_add_f32_e32 v70, 1.0, v70
	v_add_f32_e32 v71, 1.0, v71
	v_rcp_f32_e32 v68, v68
	v_rcp_f32_e32 v69, v69
	v_rcp_f32_e32 v70, v70
	v_rcp_f32_e32 v71, v71
	v_add_f32_e32 v72, 1.0, v72
	v_add_f32_e32 v73, 1.0, v73
	v_rcp_f32_e32 v72, v72
	v_rcp_f32_e32 v73, v73
	v_pk_mul_f32 v[62:63], v[62:63], v[66:67]
	v_pk_mul_f32 v[54:55], v[54:55], v[70:71]
	v_pk_mul_f32 v[58:59], v[58:59], v[62:63]
	v_pk_mul_f32 v[62:63], v[64:65], v[68:69]
	v_pk_mul_f32 v[50:51], v[50:51], v[54:55]
	v_pk_mul_f32 v[60:61], v[60:61], v[62:63]
	v_cvt_pk_f16_f32 v58, v58, v59
	v_cvt_pk_f16_f32 v59, v60, v61
	v_cvt_pk_f16_f32 v60, v50, v51
	v_pk_mul_f32 v[50:51], v[56:57], v[72:73]
	v_add_u32_e32 v74, 0x80, v145
	v_pk_mul_f32 v[50:51], v[52:53], v[50:51]
	v_mul_f32_e32 v52, 0xbfb8aa3b, v46
	v_mul_f32_e32 v53, 0xbfb8aa3b, v47
	v_exp_f32_e32 v52, v52
	v_exp_f32_e32 v53, v53
	v_cvt_pk_f16_f32 v61, v50, v51
	v_mad_i64_i32 v[50:51], s[28:29], v74, s81, v[114:115]
	v_lshl_add_u64 v[50:51], v[50:51], 0, v[116:117]
	global_store_dwordx4 v[50:51], v[58:61], off
	v_add_f32_e32 v50, 1.0, v52
	v_add_f32_e32 v51, 1.0, v53
	v_mul_f32_e32 v52, 0xbfb8aa3b, v48
	v_mul_f32_e32 v53, 0xbfb8aa3b, v49
	v_mul_f32_e32 v54, 0xbfb8aa3b, v38
	v_mul_f32_e32 v55, 0xbfb8aa3b, v39
	v_exp_f32_e32 v52, v52
	v_exp_f32_e32 v53, v53
	v_exp_f32_e32 v54, v54
	v_exp_f32_e32 v55, v55
	v_mul_f32_e32 v56, 0xbfb8aa3b, v40
	v_mul_f32_e32 v57, 0xbfb8aa3b, v41
	v_exp_f32_e32 v56, v56
	v_exp_f32_e32 v57, v57
	v_rcp_f32_e32 v50, v50
	v_rcp_f32_e32 v51, v51
	v_add_f32_e32 v52, 1.0, v52
	v_add_f32_e32 v53, 1.0, v53
	v_add_f32_e32 v54, 1.0, v54
	v_add_f32_e32 v55, 1.0, v55
	v_rcp_f32_e32 v52, v52
	v_rcp_f32_e32 v53, v53
	v_rcp_f32_e32 v54, v54
	v_rcp_f32_e32 v55, v55
	v_add_f32_e32 v56, 1.0, v56
	v_add_f32_e32 v57, 1.0, v57
	v_rcp_f32_e32 v56, v56
	v_rcp_f32_e32 v57, v57
	v_pk_mul_f32 v[46:47], v[46:47], v[50:51]
	v_pk_mul_f32 v[38:39], v[38:39], v[54:55]
; #define PG8_BAR __builtin_amdgcn_s_barrier()
; __device__ __forceinline__ float sigmoidf_(float x) { return __builtin_amdgcn_rcpf(1.f + __expf(-x)); }
; template <class Epi, class Sched, bool ALIGN_EPI = false, bool SP2 = false>
; __device__ __forceinline__ void gemm_phase(PG8_LAS unsigned char* lds, const Gemm g, const Sched& S, const Epi& E, const int tid_in) {
;     ...
;         if constexpr (!Epi::AFTER_DRAIN) { E(acc, cur, wr, wc, fr, fq); S.done(cur); }
;         if (!has_next) break;
; #pragma unroll
;         for (int a = 0; a < 2; ++a)
; #pragma unroll
;             for (int b = 0; b < 2; ++b)
; #pragma unroll
;                 for (int m = 0; m < 4; ++m)
; #pragma unroll
;                     for (int n = 0; n < 2; ++n) acc[a][b][m][n] = (f32x4){0.f, 0.f, 0.f, 0.f};
;         cur = nxt; cA = nA; cB = nB; ++ui;
;         if constexpr (ALIGN_EPI) { if (wr == 1) PG8_BAR; }
;     }
;     __device__ __forceinline__ void operator()(const pg8::f32x4 (&acc)[2][2][4][2], const pg8::Unit& uu, int wr, int wc, int fr, int fq) const {
;     ...
;             for (int m = 0; m < 4; ++m) { float o[8];
; #pragma unroll
;                 for (int n = 0; n < 2; ++n)
; #pragma unroll
;                     for (int e = 0; e < 4; ++e) { const float g = acc[ai][0][m][n][e], up = acc[ai][1][m][n][e]; o[4 * n + e] = g * sigmoidf_(g) * up; }
;                 u32x4 w; w.x = pg8::cvt_pk_bf16(o[0], o[1]); w.y = pg8::cvt_pk_bf16(o[2], o[3]); w.z = pg8::cvt_pk_bf16(o[4], o[5]); w.w = pg8::cvt_pk_bf16(o[6], o[7]);
;                 *(u32x4*)(O + (size_t)(row0 + ai * 128 + m * 16) * DFF + col) = w; }
	v_pk_mul_f32 v[42:43], v[42:43], v[46:47]
	v_pk_mul_f32 v[46:47], v[48:49], v[52:53]
	v_pk_mul_f32 v[34:35], v[34:35], v[38:39]
	v_pk_mul_f32 v[44:45], v[44:45], v[46:47]
	v_cvt_pk_f16_f32 v42, v42, v43
	v_cvt_pk_f16_f32 v43, v44, v45
	v_cvt_pk_f16_f32 v44, v34, v35
	v_pk_mul_f32 v[34:35], v[40:41], v[56:57]
	v_mul_f32_e32 v38, 0xbfb8aa3b, v22
	v_pk_mul_f32 v[34:35], v[36:37], v[34:35]
	v_mul_f32_e32 v36, 0xbfb8aa3b, v30
	v_mul_f32_e32 v37, 0xbfb8aa3b, v31
	v_exp_f32_e32 v36, v36
	v_exp_f32_e32 v37, v37
	v_cvt_pk_f16_f32 v45, v34, v35
	v_add_u32_e32 v34, 0x90, v145
	v_mad_i64_i32 v[34:35], s[28:29], v34, s81, v[114:115]
	v_lshl_add_u64 v[34:35], v[34:35], 0, v[116:117]
	global_store_dwordx4 v[34:35], v[42:45], off
	v_add_f32_e32 v34, 1.0, v36
	v_add_f32_e32 v35, 1.0, v37
	v_mul_f32_e32 v36, 0xbfb8aa3b, v32
	v_mul_f32_e32 v37, 0xbfb8aa3b, v33
	v_mul_f32_e32 v39, 0xbfb8aa3b, v23
	v_exp_f32_e32 v36, v36
	v_exp_f32_e32 v37, v37
	v_exp_f32_e32 v38, v38
	v_exp_f32_e32 v39, v39
	v_mul_f32_e32 v40, 0xbfb8aa3b, v24
	v_mul_f32_e32 v41, 0xbfb8aa3b, v25
	v_exp_f32_e32 v40, v40
	v_exp_f32_e32 v41, v41
	v_rcp_f32_e32 v34, v34
	v_rcp_f32_e32 v35, v35
	v_add_f32_e32 v36, 1.0, v36
	v_add_f32_e32 v37, 1.0, v37
	v_add_f32_e32 v38, 1.0, v38
	v_add_f32_e32 v39, 1.0, v39
	v_rcp_f32_e32 v36, v36
	v_rcp_f32_e32 v37, v37
	v_rcp_f32_e32 v38, v38
	v_rcp_f32_e32 v39, v39
	v_add_f32_e32 v40, 1.0, v40
	v_add_f32_e32 v41, 1.0, v41
	v_rcp_f32_e32 v40, v40
	v_rcp_f32_e32 v41, v41
	v_pk_mul_f32 v[30:31], v[30:31], v[34:35]
	v_pk_mul_f32 v[22:23], v[22:23], v[38:39]
	v_pk_mul_f32 v[26:27], v[26:27], v[30:31]
	v_pk_mul_f32 v[30:31], v[32:33], v[36:37]
	v_pk_mul_f32 v[18:19], v[18:19], v[22:23]
	v_pk_mul_f32 v[28:29], v[28:29], v[30:31]
	v_cvt_pk_f16_f32 v26, v26, v27
	v_cvt_pk_f16_f32 v27, v28, v29
	v_cvt_pk_f16_f32 v28, v18, v19
	v_pk_mul_f32 v[18:19], v[24:25], v[40:41]
	v_mul_f32_e32 v22, 0xbfb8aa3b, v6
	v_pk_mul_f32 v[18:19], v[20:21], v[18:19]
	v_mul_f32_e32 v20, 0xbfb8aa3b, v14
	v_mul_f32_e32 v21, 0xbfb8aa3b, v15
	v_exp_f32_e32 v20, v20
	v_exp_f32_e32 v21, v21
	v_cvt_pk_f16_f32 v29, v18, v19
	v_add_u32_e32 v18, 0xa0, v145
	v_mad_i64_i32 v[18:19], s[28:29], v18, s81, v[114:115]
	v_lshl_add_u64 v[18:19], v[18:19], 0, v[116:117]
	global_store_dwordx4 v[18:19], v[26:29], off
	v_add_f32_e32 v18, 1.0, v20
	v_add_f32_e32 v19, 1.0, v21
	v_mul_f32_e32 v20, 0xbfb8aa3b, v16
	v_mul_f32_e32 v21, 0xbfb8aa3b, v17
	v_mul_f32_e32 v23, 0xbfb8aa3b, v7
	v_exp_f32_e32 v20, v20
	v_exp_f32_e32 v21, v21
	v_exp_f32_e32 v22, v22
	v_exp_f32_e32 v23, v23
	v_mul_f32_e32 v24, 0xbfb8aa3b, v8
	v_mul_f32_e32 v25, 0xbfb8aa3b, v9
	v_exp_f32_e32 v24, v24
	v_exp_f32_e32 v25, v25
	v_rcp_f32_e32 v18, v18
	v_rcp_f32_e32 v19, v19
	v_add_f32_e32 v20, 1.0, v20
	v_add_f32_e32 v21, 1.0, v21
	v_add_f32_e32 v22, 1.0, v22
	v_add_f32_e32 v23, 1.0, v23
	v_rcp_f32_e32 v20, v20
	v_rcp_f32_e32 v21, v21
	v_rcp_f32_e32 v22, v22
	v_rcp_f32_e32 v23, v23
	v_add_f32_e32 v24, 1.0, v24
	v_add_f32_e32 v25, 1.0, v25
	v_rcp_f32_e32 v24, v24
	v_rcp_f32_e32 v25, v25
	v_pk_mul_f32 v[14:15], v[14:15], v[18:19]
	v_pk_mul_f32 v[6:7], v[6:7], v[22:23]
	v_pk_mul_f32 v[10:11], v[10:11], v[14:15]
	v_pk_mul_f32 v[14:15], v[16:17], v[20:21]
	v_pk_mul_f32 v[2:3], v[2:3], v[6:7]
	v_pk_mul_f32 v[12:13], v[12:13], v[14:15]
	v_cvt_pk_f16_f32 v10, v10, v11
	v_cvt_pk_f16_f32 v11, v12, v13
	v_cvt_pk_f16_f32 v12, v2, v3
	v_pk_mul_f32 v[2:3], v[8:9], v[24:25]
	s_and_b64 vcc, exec, s[38:39]
	v_pk_mul_f32 v[2:3], v[4:5], v[2:3]
	s_nop 0
	v_cvt_pk_f16_f32 v13, v2, v3
	v_add_u32_e32 v2, 0xb0, v145
	v_mad_i64_i32 v[2:3], s[28:29], v2, s81, v[114:115]
	v_lshl_add_u64 v[2:3], v[2:3], 0, v[116:117]
	s_mov_b64 s[28:29], -1
	global_store_dwordx4 v[2:3], v[10:13], off
	s_mov_b32 s93, 1
	s_cbranch_vccnz .LBB0_94
	s_andn2_b64 vcc, exec, s[0:1]
	s_cbranch_vccnz .LBB0_93
	s_barrier
	s_branch .LBB0_93
